# 8094 weight-conversion items moved from the layer-0 in-GEMM pool into the layer-1 in-GEMM phase (6-round workgroups convert 57 items each before their units); attention K/V staging loads issued togeth
# baseline (speedup 1.0000x reference)
.LBB0_119:
	s_or_b64 exec, exec, s[0:1]
	v_mov_b32_e32 v157, v183
	s_waitcnt lgkmcnt(0)
	s_barrier
	s_mov_b64 s[14:15], s[70:71]
	v_readfirstlane_b32 s2, v157
	s_cmpk_gt_i32 s20, 0x71
	s_cbranch_scc0 .LBB0_121
	s_mul_i32 s0, s20, 0xc2
	s_add_i32 s3, s0, 0xffffdcd2
	s_movk_i32 s0, 0xc2
	s_cbranch_execz .LBB0_122
	s_branch .LBB0_123
.LBB0_121:
	s_movk_i32 s0, 0xc2
.LBB0_122:
	s_movk_i32 s0, 0x73
	s_mul_i32 s3, s20, 0x73
.LBB0_123:
	s_ashr_i32 s72, s2, 6
	s_add_u32 s30, s14, 0x100000
	s_addc_u32 s31, s15, 0
	s_add_i32 s73, s3, 0x3200
	s_add_i32 s0, s73, s0
	s_cmpk_lg_i32 s20, 0xff
	s_cselect_b32 s33, s0, 0xd0e2
	s_bitcmp0_b32 s20, 0
	s_cselect_b64 s[74:75], -1, 0
	s_and_b64 s[0:1], s[74:75], s[82:83]
	s_andn2_b64 vcc, exec, s[0:1]
	v_and_b32_e32 v155, 63, v157
	s_cbranch_vccnz .LBB0_174
	s_add_i32 s21, s73, s72
	s_cmp_ge_i32 s21, s33
	s_cbranch_scc1 .LBB0_173
	s_mul_hi_i32 s0, s21, 0x78787879
	s_lshr_b32 s1, s0, 31
	s_ashr_i32 s0, s0, 14
	s_add_i32 s2, s0, s1
	s_mul_i32 s0, s2, 0x8800
	s_sub_i32 s24, s21, s0
	s_ashr_i32 s3, s2, 31
	s_mul_i32 s0, s2, 0x8800000
	s_mul_hi_i32 s1, s2, 0x8800000
	s_add_u32 s0, s30, s0
	s_addc_u32 s1, s31, s1
	s_cmpk_gt_i32 s24, 0x31ff
	s_cbranch_scc0 .LBB0_130
	s_cmpk_gt_u32 s24, 0x3dff
	s_cbranch_scc0 .LBB0_131
	s_cmpk_gt_u32 s24, 0x45ff
	s_cbranch_scc0 .LBB0_134
	s_cmpk_gt_u32 s24, 0x71ff
	s_cbranch_scc0 .LBB0_135
	s_add_i32 s4, s24, 0xffff8e00
	v_readlane_b32 s36, v254, 0
	s_lshr_b32 s5, s4, 6
	s_mul_i32 s6, s2, 0x2c00000
	v_readlane_b32 s42, v254, 6
	s_mul_hi_i32 s4, s2, 0x2c00000
	v_readlane_b32 s43, v254, 7
	s_add_u32 s6, s42, s6
	s_addc_u32 s7, s43, s4
	s_lshl_b32 s4, s24, 5
	s_and_b32 s4, s4, 0x7e0
	s_add_u32 s10, s0, 0x7200000
	v_readlane_b32 s37, v254, 1
	v_readlane_b32 s38, v254, 2
	v_readlane_b32 s39, v254, 3
	v_readlane_b32 s40, v254, 4
	v_readlane_b32 s41, v254, 5
	s_addc_u32 s11, s1, 0
	s_mov_b64 s[8:9], 0
	s_branch .LBB0_136

.LBB0_423:
	s_andn2_b64 vcc, exec, s[4:5]
	s_cbranch_vccnz .LBB0_420
	s_bfe_u32 s30, s29, 0x40002
	s_waitcnt vmcnt(0)
	v_mov_b32_e32 v69, v183
	s_lshl_b32 s8, s29, 5
	s_and_b32 s4, s8, 0xfffff800
	s_lshl_b32 s5, s30, 7
	v_bfe_u32 v71, v69, 6, 1
	v_and_b32_e32 v70, 15, v69
	s_or_b32 s10, s5, s4
	v_lshlrev_b32_e32 v73, 6, v71
	s_and_b32 s6, s29, 3
	v_ashrrev_i32_e32 v72, 7, v69
	v_or3_b32 v0, v73, s10, v70
	v_lshl_add_u32 v24, s6, 2, v72
	v_ashrrev_i32_e32 v1, 31, v0
	v_lshlrev_b64 v[0:1], 11, v[0:1]
	v_lshlrev_b32_e32 v22, 6, v24
	v_bfe_u32 v34, v69, 4, 2
	v_lshl_add_u64 v[0:1], s[2:3], 0, v[0:1]
	v_ashrrev_i32_e32 v23, 31, v22
	v_lshl_add_u64 v[0:1], v[22:23], 1, v[0:1]
	v_lshlrev_b32_e32 v20, 4, v34
	v_lshl_add_u64 v[0:1], v[0:1], 0, v[20:21]
	global_load_dwordx4 v[8:11], v[0:1], off
	global_load_dwordx4 v[12:15], v[0:1], off offset:64
	v_and_b32_e32 v6, 7, v69
	s_cmp_lg_u32 s30, 0
	v_ashrrev_i32_e32 v1, 3, v69
	s_cselect_b64 s[4:5], -1, 0
	v_lshlrev_b32_e32 v2, 3, v6
	v_cmp_lt_i32_e32 vcc, s25, v1
	v_mov_b32_e32 v16, 0
	s_addk_i32 s10, 0xff80
	s_lshl_b32 s9, s6, 6
	s_or_b64 s[12:13], s[4:5], vcc
	v_mov_b32_e32 v0, 0
	v_lshlrev_b32_e32 v26, 1, v2
	v_mov_b32_e32 v2, 0
	v_mov_b32_e32 v3, 0
	v_mov_b32_e32 v4, 0
	v_mov_b32_e32 v5, 0
	v_mov_b32_e32 v17, v16
	v_mov_b32_e32 v18, v16
	v_mov_b32_e32 v19, v16
	v_add_u32_e32 v160, s10, v1
	v_ashrrev_i32_e32 v161, 31, v160
	v_lshlrev_b64 v[160:161], 9, v[160:161]
	v_lshl_add_u32 v162, s9, 1, v26
	v_mov_b32_e32 v163, 0
	v_lshl_add_u64 v[160:161], v[160:161], 0, v[162:163]
	v_lshl_add_u64 v[164:165], s[16:17], 0, v[160:161]
	v_lshl_add_u64 v[166:167], s[34:35], 0, v[160:161]
	v_mov_b32_e32 v162, 0x8000
	global_load_dwordx4 v[128:131], v[164:165], off
	global_load_dwordx4 v[144:147], v[166:167], off
	v_lshl_add_u64 v[164:165], v[164:165], 0, v[162:163]
	v_lshl_add_u64 v[166:167], v[166:167], 0, v[162:163]
	global_load_dwordx4 v[132:135], v[164:165], off
	global_load_dwordx4 v[148:151], v[166:167], off
	v_lshl_add_u64 v[164:165], v[164:165], 0, v[162:163]
	v_lshl_add_u64 v[166:167], v[166:167], 0, v[162:163]
	global_load_dwordx4 v[136:139], v[164:165], off
	global_load_dwordx4 v[152:155], v[166:167], off
	v_lshl_add_u64 v[164:165], v[164:165], 0, v[162:163]
	v_lshl_add_u64 v[166:167], v[166:167], 0, v[162:163]
	global_load_dwordx4 v[140:143], v[164:165], off
	global_load_dwordx4 v[156:159], v[166:167], off
	s_waitcnt vmcnt(0)
	s_and_saveexec_b64 s[6:7], s[12:13]
	s_cbranch_execz .LBB0_426
	v_add_u32_e32 v2, s10, v1
	v_ashrrev_i32_e32 v3, 31, v2
	v_lshlrev_b64 v[2:3], 9, v[2:3]
	v_lshl_add_u64 v[4:5], s[16:17], 0, v[2:3]
	s_lshl_b32 s76, s9, 1
	v_lshl_add_u64 v[2:3], s[34:35], 0, v[2:3]
	v_lshl_add_u64 v[4:5], v[4:5], 0, s[76:77]
	v_mov_b32_e32 v27, v21
	v_lshl_add_u64 v[2:3], v[2:3], 0, s[76:77]
	v_lshl_add_u64 v[4:5], v[4:5], 0, v[26:27]
	v_lshl_add_u64 v[2:3], v[2:3], 0, v[26:27]
	v_mov_b64_e32 v[16:17], v[128:129]
	v_mov_b64_e32 v[18:19], v[130:131]
	s_nop 0
	v_mov_b64_e32 v[2:3], v[144:145]
	v_mov_b64_e32 v[4:5], v[146:147]
.LBB0_426:
	s_or_b64 exec, exec, s[6:7]
	v_lshl_add_u32 v28, v6, 4, 16
	s_movk_i32 s6, 0x1070
	v_mad_u32_u24 v25, v6, s6, v28
	v_mad_u64_u32 v[6:7], s[6:7], v1, s26, v[28:29]
	v_lshl_add_u32 v1, v1, 1, v25
	s_waitcnt vmcnt(1)
	ds_write_b128 v6, v[16:19]
	s_waitcnt vmcnt(0)
	ds_write_b16 v1, v2 offset:36864
	ds_write_b16_d16_hi v1, v2 offset:37392
	ds_write_b16 v1, v3 offset:37920
	ds_write_b16_d16_hi v1, v3 offset:38448
	ds_write_b16 v1, v4 offset:38976
	ds_write_b16_d16_hi v1, v4 offset:39504
	ds_write_b16 v1, v5 offset:40032
	ds_write_b16_d16_hi v1, v5 offset:40560
	v_add_u32_e32 v1, 0x200, v69
	v_ashrrev_i32_e32 v1, 3, v1
	v_cmp_lt_i32_e32 vcc, s25, v1
	s_or_b64 s[12:13], s[4:5], vcc
	v_mov_b32_e32 v2, 0
	v_mov_b32_e32 v3, 0
	v_mov_b32_e32 v4, 0
	v_mov_b32_e32 v5, 0
	v_mov_b32_e32 v16, 0
	v_mov_b32_e32 v17, 0
	v_mov_b32_e32 v18, 0
	v_mov_b32_e32 v19, 0
	s_and_saveexec_b64 s[6:7], s[12:13]
	s_cbranch_execz .LBB0_428
	v_add_u32_e32 v2, s10, v1
	v_ashrrev_i32_e32 v3, 31, v2
	v_lshlrev_b64 v[2:3], 9, v[2:3]
	v_lshl_add_u64 v[4:5], s[16:17], 0, v[2:3]
	s_lshl_b32 s76, s9, 1
	v_lshl_add_u64 v[2:3], s[34:35], 0, v[2:3]
	v_lshl_add_u64 v[4:5], v[4:5], 0, s[76:77]
	v_mov_b32_e32 v27, v21
	v_lshl_add_u64 v[2:3], v[2:3], 0, s[76:77]
	v_lshl_add_u64 v[4:5], v[4:5], 0, v[26:27]
	v_lshl_add_u64 v[2:3], v[2:3], 0, v[26:27]
	v_mov_b64_e32 v[16:17], v[132:133]
	v_mov_b64_e32 v[18:19], v[134:135]
	s_nop 0
	v_mov_b64_e32 v[2:3], v[148:149]
	v_mov_b64_e32 v[4:5], v[150:151]
.LBB0_428:
	s_or_b64 exec, exec, s[6:7]
	v_mad_u64_u32 v[6:7], s[6:7], v1, s26, v[28:29]
	v_lshl_add_u32 v1, v1, 1, v25
	s_waitcnt vmcnt(1)
	ds_write_b128 v6, v[16:19]
	s_waitcnt vmcnt(0)
	ds_write_b16 v1, v2 offset:36864
	ds_write_b16_d16_hi v1, v2 offset:37392
	ds_write_b16 v1, v3 offset:37920
	ds_write_b16_d16_hi v1, v3 offset:38448
	ds_write_b16 v1, v4 offset:38976
	ds_write_b16_d16_hi v1, v4 offset:39504
	ds_write_b16 v1, v5 offset:40032
	ds_write_b16_d16_hi v1, v5 offset:40560
	v_add_u32_e32 v1, 0x400, v69
	v_ashrrev_i32_e32 v5, 3, v1
	v_cmp_lt_i32_e32 vcc, s25, v5
	s_or_b64 s[12:13], s[4:5], vcc
	v_mov_b32_e32 v4, 0
	v_mov_b32_e32 v16, 0
	v_mov_b32_e32 v17, 0
	v_mov_b32_e32 v18, 0
	v_mov_b32_e32 v19, 0
	v_mov_b32_e32 v1, 0
	v_mov_b32_e32 v2, 0
	v_mov_b32_e32 v3, 0
	s_and_saveexec_b64 s[6:7], s[12:13]
	s_cbranch_execz .LBB0_430
	v_add_u32_e32 v0, s10, v5
	v_ashrrev_i32_e32 v1, 31, v0
	v_lshlrev_b64 v[0:1], 9, v[0:1]
	v_lshl_add_u64 v[2:3], s[16:17], 0, v[0:1]
	s_lshl_b32 s76, s9, 1
	v_lshl_add_u64 v[2:3], v[2:3], 0, s[76:77]
	v_mov_b32_e32 v27, v21
	v_lshl_add_u64 v[0:1], s[34:35], 0, v[0:1]
	v_lshl_add_u64 v[2:3], v[2:3], 0, v[26:27]
	v_lshl_add_u64 v[0:1], v[0:1], 0, s[76:77]
	v_lshl_add_u64 v[6:7], v[0:1], 0, v[26:27]
	v_mov_b64_e32 v[0:1], v[136:137]
	v_mov_b64_e32 v[2:3], v[138:139]
	s_nop 0
	v_mov_b64_e32 v[16:17], v[152:153]
	v_mov_b64_e32 v[18:19], v[154:155]
.LBB0_430:
	s_or_b64 exec, exec, s[6:7]
	v_mad_u64_u32 v[6:7], s[6:7], v5, s26, v[28:29]
	s_waitcnt vmcnt(1)
	ds_write_b128 v6, v[0:3]
	v_lshl_add_u32 v0, v5, 1, v25
	s_waitcnt vmcnt(0)
	ds_write_b16 v0, v16 offset:36864
	ds_write_b16_d16_hi v0, v16 offset:37392
	ds_write_b16 v0, v17 offset:37920
	ds_write_b16_d16_hi v0, v17 offset:38448
	ds_write_b16 v0, v18 offset:38976
	ds_write_b16_d16_hi v0, v18 offset:39504
	ds_write_b16 v0, v19 offset:40032
	ds_write_b16_d16_hi v0, v19 offset:40560
	v_add_u32_e32 v0, 0x600, v69
	v_ashrrev_i32_e32 v16, 3, v0
	v_cmp_lt_i32_e32 vcc, s25, v16
	s_or_b64 s[6:7], s[4:5], vcc
	v_mov_b32_e32 v5, 0
	v_mov_b32_e32 v6, 0
	v_mov_b32_e32 v7, 0
	v_mov_b32_e32 v0, 0
	v_mov_b32_e32 v1, 0
	v_mov_b32_e32 v2, 0
	v_mov_b32_e32 v3, 0
	s_and_saveexec_b64 s[4:5], s[6:7]
	s_cbranch_execz .LBB0_432
	v_add_u32_e32 v0, s10, v16
	v_ashrrev_i32_e32 v1, 31, v0
	v_lshlrev_b64 v[0:1], 9, v[0:1]
	v_lshl_add_u64 v[2:3], s[16:17], 0, v[0:1]
	s_lshl_b32 s76, s9, 1
	v_lshl_add_u64 v[0:1], s[34:35], 0, v[0:1]
	v_lshl_add_u64 v[2:3], v[2:3], 0, s[76:77]
	v_mov_b32_e32 v27, v21
	v_lshl_add_u64 v[0:1], v[0:1], 0, s[76:77]
	v_lshl_add_u64 v[2:3], v[2:3], 0, v[26:27]
	v_lshl_add_u64 v[4:5], v[0:1], 0, v[26:27]
	v_mov_b64_e32 v[0:1], v[140:141]
	v_mov_b64_e32 v[2:3], v[142:143]
	s_nop 0
	v_mov_b64_e32 v[4:5], v[156:157]
	v_mov_b64_e32 v[6:7], v[158:159]

.LBB0_1157:
	s_or_b64 exec, exec, s[0:1]
	v_mov_b32_e32 v157, v183
	s_mov_b64 s[14:15], s[70:71]
	v_readfirstlane_b32 s2, v157
	s_cmpk_gt_i32 s20, 0x71
	s_cbranch_scc0 .Lcvb_121
	s_mul_i32 s0, s20, 0x39
	s_add_i32 s3, s0, 0xffffe69e
	s_movk_i32 s0, 0x39
	s_cbranch_execz .Lcvb_122
	s_branch .Lcvb_123
.Lcvb_121:
	s_movk_i32 s0, 0x39
.Lcvb_122:
	s_movk_i32 s0, 0
	s_mul_i32 s3, s20, 0
.Lcvb_123:
	s_ashr_i32 s72, s2, 6
	s_add_u32 s30, s14, 0x100000
	s_addc_u32 s31, s15, 0
	s_add_i32 s73, s3, 0xd0e2
	s_add_i32 s0, s73, s0
	s_cmpk_lg_i32 s20, 0xff
	s_cselect_b32 s33, s0, 0xf080
	s_cmp_eq_u32 s20, s20
	s_cselect_b64 s[74:75], -1, 0
	s_cmp_eq_u32 s22, 0x100
	s_cselect_b64 s[0:1], -1, 0
	s_andn2_b64 vcc, exec, s[0:1]
	v_and_b32_e32 v155, 63, v157
	s_cbranch_vccnz .Lcvb_end
	s_add_i32 s21, s73, s72
	s_cmp_ge_i32 s21, s33
	s_cbranch_scc1 .Lcvb_173
	s_mul_hi_i32 s0, s21, 0x78787879
	s_lshr_b32 s1, s0, 31
	s_ashr_i32 s0, s0, 14
	s_add_i32 s2, s0, s1
	s_mul_i32 s0, s2, 0x8800
	s_sub_i32 s24, s21, s0
	s_ashr_i32 s3, s2, 31
	s_mul_i32 s0, s2, 0x8800000
	s_mul_hi_i32 s1, s2, 0x8800000
	s_add_u32 s0, s30, s0
	s_addc_u32 s1, s31, s1
	s_cmpk_gt_i32 s24, 0x31ff
	s_cbranch_scc0 .Lcvb_130
	s_cmpk_gt_u32 s24, 0x3dff
	s_cbranch_scc0 .Lcvb_131
	s_cmpk_gt_u32 s24, 0x45ff
	s_cbranch_scc0 .Lcvb_134
	s_cmpk_gt_u32 s24, 0x71ff
	s_cbranch_scc0 .Lcvb_135
	s_add_i32 s4, s24, 0xffff8e00
	v_readlane_b32 s36, v254, 0
	s_lshr_b32 s5, s4, 6
	s_mul_i32 s6, s2, 0x2c00000
	v_readlane_b32 s42, v254, 6
	s_mul_hi_i32 s4, s2, 0x2c00000
	v_readlane_b32 s43, v254, 7
	s_add_u32 s6, s42, s6
	s_addc_u32 s7, s43, s4
	s_lshl_b32 s4, s24, 5
	s_and_b32 s4, s4, 0x7e0
	s_add_u32 s10, s0, 0x7200000
	v_readlane_b32 s37, v254, 1
	v_readlane_b32 s38, v254, 2
	v_readlane_b32 s39, v254, 3
	v_readlane_b32 s40, v254, 4
	v_readlane_b32 s41, v254, 5
	s_addc_u32 s11, s1, 0
	s_mov_b64 s[8:9], 0
	s_branch .Lcvb_136

.Lcvb_131:
	s_branch .Lcvb_142
.Lcvb_134:
	s_mov_b64 s[16:17], -1
	s_branch .Lcvb_139

.Lcvb_end:
	v_readlane_b32 s0, v254, 48
	s_waitcnt lgkmcnt(0)
	v_mov_b32_e32 v0, v183
	s_mov_b64 s[26:27], s[70:71]
	v_mov_b32_e32 v9, v183
	v_readlane_b32 s1, v254, 49
	s_barrier
	s_and_b64 vcc, exec, s[0:1]
	v_readfirstlane_b32 s2, v9
	s_cbranch_vccnz .LBB0_1163
	s_ashr_i32 s0, s20, 31
	s_lshr_b32 s0, s0, 29
	s_add_i32 s3, s20, s0
	s_and_b32 s0, s3, -8
	s_sub_i32 s4, s20, s0
	s_cmp_gt_i32 s4, 1
	s_cbranch_scc0 .LBB0_1160
	s_mul_i32 s0, s4, 0xce
	s_add_i32 s5, s0, 2
	s_cbranch_execz .LBB0_1161
	s_branch .LBB0_1162

.LBB0_1358:
	s_andn2_b64 vcc, exec, s[2:3]
	s_cbranch_vccnz .LBB0_1355
	s_bfe_u32 s59, s58, 0x40002
	v_mov_b32_e32 v69, v183
	s_lshl_b32 s10, s58, 5
	s_and_b32 s2, s10, 0xfffff800
	s_lshl_b32 s3, s59, 7
	v_bfe_u32 v71, v69, 6, 1
	v_and_b32_e32 v70, 15, v69
	s_or_b32 s12, s3, s2
	v_lshlrev_b32_e32 v73, 6, v71
	s_and_b32 s8, s58, 3
	v_ashrrev_i32_e32 v72, 7, v69
	v_or3_b32 v0, v73, s12, v70
	v_lshl_add_u32 v24, s8, 2, v72
	v_ashrrev_i32_e32 v1, 31, v0
	v_lshlrev_b64 v[0:1], 11, v[0:1]
	v_lshlrev_b32_e32 v22, 6, v24
	v_bfe_u32 v34, v69, 4, 2
	v_lshl_add_u64 v[0:1], s[4:5], 0, v[0:1]
	v_ashrrev_i32_e32 v23, 31, v22
	v_lshl_add_u64 v[0:1], v[22:23], 1, v[0:1]
	v_lshlrev_b32_e32 v20, 4, v34
	v_lshl_add_u64 v[0:1], v[0:1], 0, v[20:21]
	global_load_dwordx4 v[8:11], v[0:1], off
	global_load_dwordx4 v[12:15], v[0:1], off offset:64
	v_and_b32_e32 v6, 7, v69
	s_cmp_lg_u32 s59, 0
	v_ashrrev_i32_e32 v1, 3, v69
	s_cselect_b64 s[2:3], -1, 0
	v_lshlrev_b32_e32 v2, 3, v6
	v_cmp_lt_i32_e32 vcc, s52, v1
	v_mov_b32_e32 v16, 0
	s_addk_i32 s12, 0xff80
	s_lshl_b32 s11, s8, 6
	s_or_b64 s[14:15], s[2:3], vcc
	v_mov_b32_e32 v0, 0
	v_lshlrev_b32_e32 v26, 1, v2
	v_mov_b32_e32 v2, 0
	v_mov_b32_e32 v3, 0
	v_mov_b32_e32 v4, 0
	v_mov_b32_e32 v5, 0
	v_mov_b32_e32 v17, v16
	v_mov_b32_e32 v18, v16
	v_mov_b32_e32 v19, v16
	v_add_u32_e32 v160, s12, v1
	v_ashrrev_i32_e32 v161, 31, v160
	v_lshlrev_b64 v[160:161], 9, v[160:161]
	v_lshl_add_u32 v162, s11, 1, v26
	v_mov_b32_e32 v163, 0
	v_lshl_add_u64 v[160:161], v[160:161], 0, v[162:163]
	v_lshl_add_u64 v[164:165], s[6:7], 0, v[160:161]
	v_lshl_add_u64 v[166:167], s[26:27], 0, v[160:161]
	v_mov_b32_e32 v162, 0x8000
	global_load_dwordx4 v[128:131], v[164:165], off
	global_load_dwordx4 v[144:147], v[166:167], off
	v_lshl_add_u64 v[164:165], v[164:165], 0, v[162:163]
	v_lshl_add_u64 v[166:167], v[166:167], 0, v[162:163]
	global_load_dwordx4 v[132:135], v[164:165], off
	global_load_dwordx4 v[148:151], v[166:167], off
	v_lshl_add_u64 v[164:165], v[164:165], 0, v[162:163]
	v_lshl_add_u64 v[166:167], v[166:167], 0, v[162:163]
	global_load_dwordx4 v[136:139], v[164:165], off
	global_load_dwordx4 v[152:155], v[166:167], off
	v_lshl_add_u64 v[164:165], v[164:165], 0, v[162:163]
	v_lshl_add_u64 v[166:167], v[166:167], 0, v[162:163]
	global_load_dwordx4 v[140:143], v[164:165], off
	global_load_dwordx4 v[156:159], v[166:167], off
	s_waitcnt vmcnt(0)
	s_and_saveexec_b64 s[8:9], s[14:15]
	s_cbranch_execz .LBB0_1361
	v_add_u32_e32 v2, s12, v1
	v_ashrrev_i32_e32 v3, 31, v2
	v_lshlrev_b64 v[2:3], 9, v[2:3]
	v_lshl_add_u64 v[4:5], s[6:7], 0, v[2:3]
	s_lshl_b32 s48, s11, 1
	v_lshl_add_u64 v[2:3], s[26:27], 0, v[2:3]
	v_lshl_add_u64 v[4:5], v[4:5], 0, s[48:49]
	v_mov_b32_e32 v27, v21
	v_lshl_add_u64 v[2:3], v[2:3], 0, s[48:49]
	v_lshl_add_u64 v[4:5], v[4:5], 0, v[26:27]
	v_lshl_add_u64 v[2:3], v[2:3], 0, v[26:27]
	v_mov_b64_e32 v[16:17], v[128:129]
	v_mov_b64_e32 v[18:19], v[130:131]
	s_nop 0
	v_mov_b64_e32 v[2:3], v[144:145]
	v_mov_b64_e32 v[4:5], v[146:147]
.LBB0_1361:
	s_or_b64 exec, exec, s[8:9]
	v_lshl_add_u32 v28, v6, 4, 16
	s_movk_i32 s8, 0x1070
	v_mad_u32_u24 v25, v6, s8, v28
	v_mad_u64_u32 v[6:7], s[8:9], v1, s53, v[28:29]
	v_lshl_add_u32 v1, v1, 1, v25
	s_waitcnt vmcnt(0)
	ds_write_b128 v6, v[16:19]
	ds_write_b16 v1, v2 offset:36864
	ds_write_b16_d16_hi v1, v2 offset:37392
	ds_write_b16 v1, v3 offset:37920
	ds_write_b16_d16_hi v1, v3 offset:38448
	ds_write_b16 v1, v4 offset:38976
	ds_write_b16_d16_hi v1, v4 offset:39504
	ds_write_b16 v1, v5 offset:40032
	ds_write_b16_d16_hi v1, v5 offset:40560
	v_add_u32_e32 v1, 0x200, v69
	v_ashrrev_i32_e32 v1, 3, v1
	v_cmp_lt_i32_e32 vcc, s52, v1
	s_or_b64 s[14:15], s[2:3], vcc
	v_mov_b32_e32 v2, 0
	v_mov_b32_e32 v3, 0
	v_mov_b32_e32 v4, 0
	v_mov_b32_e32 v5, 0
	v_mov_b32_e32 v16, 0
	v_mov_b32_e32 v17, 0
	v_mov_b32_e32 v18, 0
	v_mov_b32_e32 v19, 0
	s_and_saveexec_b64 s[8:9], s[14:15]
	s_cbranch_execz .LBB0_1363
	v_add_u32_e32 v2, s12, v1
	v_ashrrev_i32_e32 v3, 31, v2
	v_lshlrev_b64 v[2:3], 9, v[2:3]
	v_lshl_add_u64 v[4:5], s[6:7], 0, v[2:3]
	s_lshl_b32 s48, s11, 1
	v_lshl_add_u64 v[2:3], s[26:27], 0, v[2:3]
	v_lshl_add_u64 v[4:5], v[4:5], 0, s[48:49]
	v_mov_b32_e32 v27, v21
	v_lshl_add_u64 v[2:3], v[2:3], 0, s[48:49]
	v_lshl_add_u64 v[4:5], v[4:5], 0, v[26:27]
	v_lshl_add_u64 v[2:3], v[2:3], 0, v[26:27]
	v_mov_b64_e32 v[16:17], v[132:133]
	v_mov_b64_e32 v[18:19], v[134:135]
	s_nop 0
	v_mov_b64_e32 v[2:3], v[148:149]
	v_mov_b64_e32 v[4:5], v[150:151]
.LBB0_1363:
	s_or_b64 exec, exec, s[8:9]
	v_mad_u64_u32 v[6:7], s[8:9], v1, s53, v[28:29]
	v_lshl_add_u32 v1, v1, 1, v25
	s_waitcnt vmcnt(1)
	ds_write_b128 v6, v[16:19]
	s_waitcnt vmcnt(0)
	ds_write_b16 v1, v2 offset:36864
	ds_write_b16_d16_hi v1, v2 offset:37392
	ds_write_b16 v1, v3 offset:37920
	ds_write_b16_d16_hi v1, v3 offset:38448
	ds_write_b16 v1, v4 offset:38976
	ds_write_b16_d16_hi v1, v4 offset:39504
	ds_write_b16 v1, v5 offset:40032
	ds_write_b16_d16_hi v1, v5 offset:40560
	v_add_u32_e32 v1, 0x400, v69
	v_ashrrev_i32_e32 v5, 3, v1
	v_cmp_lt_i32_e32 vcc, s52, v5
	s_or_b64 s[14:15], s[2:3], vcc
	v_mov_b32_e32 v4, 0
	v_mov_b32_e32 v16, 0
	v_mov_b32_e32 v17, 0
	v_mov_b32_e32 v18, 0
	v_mov_b32_e32 v19, 0
	v_mov_b32_e32 v1, 0
	v_mov_b32_e32 v2, 0
	v_mov_b32_e32 v3, 0
	s_and_saveexec_b64 s[8:9], s[14:15]
	s_cbranch_execz .LBB0_1365
	v_add_u32_e32 v0, s12, v5
	v_ashrrev_i32_e32 v1, 31, v0
	v_lshlrev_b64 v[0:1], 9, v[0:1]
	v_lshl_add_u64 v[2:3], s[6:7], 0, v[0:1]
	s_lshl_b32 s48, s11, 1
	v_lshl_add_u64 v[2:3], v[2:3], 0, s[48:49]
	v_mov_b32_e32 v27, v21
	v_lshl_add_u64 v[0:1], s[26:27], 0, v[0:1]
	v_lshl_add_u64 v[2:3], v[2:3], 0, v[26:27]
	v_lshl_add_u64 v[0:1], v[0:1], 0, s[48:49]
	v_lshl_add_u64 v[6:7], v[0:1], 0, v[26:27]
	v_mov_b64_e32 v[0:1], v[136:137]
	v_mov_b64_e32 v[2:3], v[138:139]
	s_nop 0
	v_mov_b64_e32 v[16:17], v[152:153]
	v_mov_b64_e32 v[18:19], v[154:155]
.LBB0_1365:
	s_or_b64 exec, exec, s[8:9]
	v_mad_u64_u32 v[6:7], s[8:9], v5, s53, v[28:29]
	s_waitcnt vmcnt(1)
	ds_write_b128 v6, v[0:3]
	v_lshl_add_u32 v0, v5, 1, v25
	s_waitcnt vmcnt(0)
	ds_write_b16 v0, v16 offset:36864
	ds_write_b16_d16_hi v0, v16 offset:37392
	ds_write_b16 v0, v17 offset:37920
	ds_write_b16_d16_hi v0, v17 offset:38448
	ds_write_b16 v0, v18 offset:38976
	ds_write_b16_d16_hi v0, v18 offset:39504
	ds_write_b16 v0, v19 offset:40032
	ds_write_b16_d16_hi v0, v19 offset:40560
	v_add_u32_e32 v0, 0x600, v69
	v_ashrrev_i32_e32 v16, 3, v0
	v_cmp_lt_i32_e32 vcc, s52, v16
	s_or_b64 s[8:9], s[2:3], vcc
	v_mov_b32_e32 v5, 0
	v_mov_b32_e32 v6, 0
	v_mov_b32_e32 v7, 0
	v_mov_b32_e32 v0, 0
	v_mov_b32_e32 v1, 0
	v_mov_b32_e32 v2, 0
	v_mov_b32_e32 v3, 0
	s_and_saveexec_b64 s[2:3], s[8:9]
	s_cbranch_execz .LBB0_1367
	v_add_u32_e32 v0, s12, v16
	v_ashrrev_i32_e32 v1, 31, v0
	v_lshlrev_b64 v[0:1], 9, v[0:1]
	v_lshl_add_u64 v[2:3], s[6:7], 0, v[0:1]
	s_lshl_b32 s48, s11, 1
	v_lshl_add_u64 v[0:1], s[26:27], 0, v[0:1]
	v_lshl_add_u64 v[2:3], v[2:3], 0, s[48:49]
	v_mov_b32_e32 v27, v21
	v_lshl_add_u64 v[0:1], v[0:1], 0, s[48:49]
	v_lshl_add_u64 v[2:3], v[2:3], 0, v[26:27]
	v_lshl_add_u64 v[4:5], v[0:1], 0, v[26:27]
	v_mov_b64_e32 v[0:1], v[140:141]
	v_mov_b64_e32 v[2:3], v[142:143]
	s_nop 0
	v_mov_b64_e32 v[4:5], v[156:157]
	v_mov_b64_e32 v[6:7], v[158:159]
